# attention key loop: iteration top reordered - current-stage addresses + K reads first, next-tile LDS-DMA/V-load setup after
# baseline (speedup 1.0000x reference)
; #define SB_ __builtin_amdgcn_sched_barrier(0)
; DI void attn_item64(const Params& p, int it, char* smem) {
;     ...
;   for (int kt = 0; kt < NKT; ++kt) {
;     const char* cur = smem + (kt & 1) * STAGE;
;     const bool more = kt + 1 < NKT;
;     if (more) {
;       const bf16_t* kn = Kb + (size_t)(kt + 1) * 64 * QKD; const bf16_t* vn = Vb + (kt + 1) * 64;
;       char* nx = smem + ((kt + 1) & 1) * STAGE;
;       GLDS(kn + kgo0, nx + klo0); if (k1v) GLDS(kn + kgo1, nx + klo1);
;       rv0 = *(const uint4*)(vn + vgo0);
;     }
;     SB_;
; #pragma unroll
;     for (int t2 = 0; t2 < 2; ++t2) {
;       const char* kpe = cur + (t2 * 32 + r) * KROW + swo;
;       const char* kpo = kpe - 2 * sb32;
;       f32x16 sa, sb;
;       { const bf16x8 kf = *(const bf16x8*)(kpe); sa = MFMA(kf, qfa[0], sinit); sb = MFMA(kf, qfb[0], sinit); }
; #pragma unroll
;       for (int c = 1; c < 6; ++c) { const bf16x8 kf = *(const bf16x8*)(((c & 1) ? kpo : kpe) + c * 32); sa = MFMA(kf, qfa[c], sa); sb = MFMA(kf, qfb[c], sb); }
;       SB_;
;       float lsa = 0.f, lsb = 0.f;
; #pragma unroll
;       for (int i = 0; i < 16; ++i) { const float e = __builtin_amdgcn_exp2f(sa[i]); sa[i] = e; lsa += e; const float f = __builtin_amdgcn_exp2f(sb[i]); sb[i] = f; lsb += f; }
;       la += lsa; lb += lsb;
;       SB_;
; #pragma unroll
;       for (int s2 = 0; s2 < 2; ++s2) {
;         uint4 pu, pv;
;         pu.x = pk_bf16(sa[8 * s2 + 0], sa[8 * s2 + 1]); pu.y = pk_bf16(sa[8 * s2 + 2], sa[8 * s2 + 3]); pu.z = pk_bf16(sa[8 * s2 + 4], sa[8 * s2 + 5]); pu.w = pk_bf16(sa[8 * s2 + 6], sa[8 * s2 + 7]);
;         pv.x = pk_bf16(sb[8 * s2 + 0], sb[8 * s2 + 1]); pv.y = pk_bf16(sb[8 * s2 + 2], sb[8 * s2 + 3]); pv.z = pk_bf16(sb[8 * s2 + 4], sb[8 * s2 + 5]); pv.w = pk_bf16(sb[8 * s2 + 6], sb[8 * s2 + 7]);
;         const bf16x8 pa_ = __builtin_bit_cast(bf16x8, pu), pb_ = __builtin_bit_cast(bf16x8, pv);
; #pragma unroll
;         for (int vt = 0; vt < 2; ++vt) {
;           const char* vp = cur + KBYTES + (vt * 32 + r) * VROW + (t2 * 32 + 16 * s2 + 4 * hh) * 2;
;           const uint2 lo = *(const uint2*)(vp), hi = *(const uint2*)(vp + 16);
;           uint4 vu; vu.x = lo.x; vu.y = lo.y; vu.z = hi.x; vu.w = hi.y;
;           const bf16x8 vf = __builtin_bit_cast(bf16x8, vu);
;           oa[vt] = MFMA(vf, pa_, oa[vt]);
;           ob[vt] = MFMA(vf, pb_, ob[vt]);
;         }
;       }
.LBB0_548:
	s_or_b64 exec, exec, s[4:5]
	global_load_dwordx4 v[160:163], v[170:171], off
	s_waitcnt lgkmcnt(4)
	v_mfma_f32_32x32x16_bf16 v[80:95], v[176:179], v[152:155], v[64:79]
	v_mfma_f32_32x32x16_bf16 v[96:111], v[176:179], v[156:159], v[64:79]
	ds_read_b128 v[176:179], v188 offset:160
	s_waitcnt lgkmcnt(4)
	v_mfma_f32_32x32x16_bf16 v[80:95], v[242:245], v[136:139], v[80:95]
	v_mfma_f32_32x32x16_bf16 v[96:111], v[242:245], v[140:143], v[96:111]
	s_waitcnt lgkmcnt(3)
	v_mfma_f32_32x32x16_bf16 v[80:95], v[180:183], v[144:147], v[80:95]
	v_mfma_f32_32x32x16_bf16 v[96:111], v[180:183], v[148:151], v[96:111]
	s_waitcnt lgkmcnt(2)
	v_mfma_f32_32x32x16_bf16 v[80:95], v[246:249], v[112:115], v[80:95]
	v_mfma_f32_32x32x16_bf16 v[96:111], v[246:249], v[124:127], v[96:111]
	s_waitcnt lgkmcnt(1)
	v_mfma_f32_32x32x16_bf16 v[80:95], v[184:187], v[128:131], v[80:95]
	v_mfma_f32_32x32x16_bf16 v[96:111], v[184:187], v[132:135], v[96:111]
	s_waitcnt lgkmcnt(0)
	v_mfma_f32_32x32x16_bf16 v[80:95], v[176:179], v[116:119], v[80:95]
	v_mfma_f32_32x32x16_bf16 v[96:111], v[176:179], v[120:123], v[96:111]
	v_add_u32_e32 v239, 0x3000, v195
	v_add_u32_e32 v240, 0x4000, v195
	ds_read2_b64 v[242:245], v239 offset1:2
	ds_read2_b64 v[246:249], v240 offset0:32 offset1:34
	s_nop 10
	v_exp_f32_e32 v214, v80
	v_exp_f32_e32 v215, v81
	v_exp_f32_e32 v216, v82
	v_exp_f32_e32 v217, v83
	v_add_f32_e32 v80, 0, v214
	v_exp_f32_e32 v218, v84
	v_add_f32_e32 v80, v215, v80
	v_exp_f32_e32 v219, v85
	v_add_f32_e32 v80, v216, v80
	v_exp_f32_e32 v222, v86
	v_add_f32_e32 v80, v217, v80
	v_add_f32_e32 v80, v218, v80
	v_add_f32_e32 v80, v219, v80
	v_exp_f32_e32 v96, v96
	v_exp_f32_e32 v97, v97
	v_exp_f32_e32 v98, v98
	v_exp_f32_e32 v99, v99
	v_exp_f32_e32 v100, v100
	v_exp_f32_e32 v101, v101
	v_exp_f32_e32 v102, v102
	v_exp_f32_e32 v188, v87
	v_exp_f32_e32 v189, v103
	v_exp_f32_e32 v186, v88
	v_exp_f32_e32 v187, v104
	v_exp_f32_e32 v190, v89
	v_exp_f32_e32 v191, v105
	v_exp_f32_e32 v192, v90
	v_exp_f32_e32 v193, v106
	v_exp_f32_e32 v180, v91
	v_exp_f32_e32 v181, v107
	v_exp_f32_e32 v182, v92
	v_exp_f32_e32 v183, v108
	v_exp_f32_e32 v184, v93
	v_exp_f32_e32 v185, v109
	v_exp_f32_e32 v176, v94
	v_exp_f32_e32 v177, v110
	v_exp_f32_e32 v178, v95
	v_exp_f32_e32 v179, v111
	v_add_f32_e32 v194, v222, v80
	v_cvt_pk_bf16_f32 v84, v214, v215
	v_cvt_pk_bf16_f32 v85, v216, v217
	v_cvt_pk_bf16_f32 v86, v218, v219
	v_cvt_pk_bf16_f32 v87, v222, v188
	v_cvt_pk_bf16_f32 v88, v96, v97
	v_cvt_pk_bf16_f32 v89, v98, v99
	v_cvt_pk_bf16_f32 v90, v100, v101
	v_cvt_pk_bf16_f32 v91, v102, v189
	s_waitcnt lgkmcnt(0)
	v_mfma_f32_32x32x16_bf16 v[48:63], v[242:245], v[84:87], v[48:63]
	v_mfma_f32_32x32x16_bf16 v[32:47], v[242:245], v[88:91], v[32:47]
	ds_read2_b64 v[214:217], v239 offset0:4 offset1:6
	ds_read2_b64 v[222:225], v240 offset0:36 offset1:38
	s_waitcnt lgkmcnt(2)
	v_mfma_f32_32x32x16_bf16 v[16:31], v[246:249], v[84:87], v[16:31]
	v_add_f32_e32 v84, 0, v96
	v_add_f32_e32 v84, v97, v84
	v_add_f32_e32 v84, v98, v84
	v_add_f32_e32 v84, v99, v84
	v_add_f32_e32 v84, v100, v84
	v_add_f32_e32 v84, v101, v84
	v_add_f32_e32 v195, v102, v84
	v_mfma_f32_32x32x16_bf16 v[0:15], v[246:249], v[88:91], v[0:15]
	ds_read_b128 v[226:229], v168 offset:6144
	ds_read_b128 v[242:245], v213 offset:32
	ds_read_b128 v[230:233], v168 offset:6208
	ds_read_b128 v[246:249], v213 offset:96
	ds_read_b128 v[234:237], v168 offset:6272
	s_waitcnt lgkmcnt(4)
	v_mfma_f32_32x32x16_bf16 v[80:95], v[226:229], v[152:155], v[64:79]
	v_mfma_f32_32x32x16_bf16 v[96:111], v[226:229], v[156:159], v[64:79]
	ds_read_b128 v[226:229], v213 offset:160
	s_waitcnt lgkmcnt(4)
	v_mfma_f32_32x32x16_bf16 v[80:95], v[242:245], v[136:139], v[80:95]
	v_mfma_f32_32x32x16_bf16 v[96:111], v[242:245], v[140:143], v[96:111]
	s_waitcnt lgkmcnt(3)
	v_mfma_f32_32x32x16_bf16 v[80:95], v[230:233], v[144:147], v[80:95]
	v_mfma_f32_32x32x16_bf16 v[96:111], v[230:233], v[148:151], v[96:111]
	s_waitcnt lgkmcnt(2)
	v_mfma_f32_32x32x16_bf16 v[80:95], v[246:249], v[112:115], v[80:95]
	v_mfma_f32_32x32x16_bf16 v[96:111], v[246:249], v[124:127], v[96:111]
	s_waitcnt lgkmcnt(1)
	v_mfma_f32_32x32x16_bf16 v[80:95], v[234:237], v[128:131], v[80:95]
	v_mfma_f32_32x32x16_bf16 v[96:111], v[234:237], v[132:135], v[96:111]
	s_waitcnt lgkmcnt(0)
	v_mfma_f32_32x32x16_bf16 v[80:95], v[226:229], v[116:119], v[80:95]
	v_mfma_f32_32x32x16_bf16 v[96:111], v[226:229], v[120:123], v[96:111]
	s_waitcnt vmcnt(0)
; #define MFMA(a, b, c) __builtin_amdgcn_mfma_f32_32x32x16_bf16((a), (b), (c), 0, 0, 0)
; DI void attn_item64(const Params& p, int it, char* smem) {
;     ...
;   for (int kt = 0; kt < NKT; ++kt) {
;     const char* cur = smem + (kt & 1) * STAGE;
;     const bool more = kt + 1 < NKT;
;     if (more) {
;       const bf16_t* kn = Kb + (size_t)(kt + 1) * 64 * QKD; const bf16_t* vn = Vb + (kt + 1) * 64;
;       char* nx = smem + ((kt + 1) & 1) * STAGE;
;       GLDS(kn + kgo0, nx + klo0); if (k1v) GLDS(kn + kgo1, nx + klo1);
;       rv0 = *(const uint4*)(vn + vgo0);
;     }
;     ...
;       { const bf16x8 kf = *(const bf16x8*)(kpe); sa = MFMA(kf, qfa[0], sinit); sb = MFMA(kf, qfb[0], sinit); }
; #pragma unroll
;       for (int c = 1; c < 6; ++c) { const bf16x8 kf = *(const bf16x8*)(((c & 1) ? kpo : kpe) + c * 32); sa = MFMA(kf, qfa[c], sa); sb = MFMA(kf, qfb[c], sb); }
;       SB_;
;       float lsa = 0.f, lsb = 0.f;
; #pragma unroll
;       for (int i = 0; i < 16; ++i) { const float e = __builtin_amdgcn_exp2f(sa[i]); sa[i] = e; lsa += e; const float f = __builtin_amdgcn_exp2f(sb[i]); sb[i] = f; lsb += f; }
;       la += lsa; lb += lsb;
;       SB_;
; #pragma unroll
;       for (int s2 = 0; s2 < 2; ++s2) {
;         uint4 pu, pv;
;         pu.x = pk_bf16(sa[8 * s2 + 0], sa[8 * s2 + 1]); pu.y = pk_bf16(sa[8 * s2 + 2], sa[8 * s2 + 3]); pu.z = pk_bf16(sa[8 * s2 + 4], sa[8 * s2 + 5]); pu.w = pk_bf16(sa[8 * s2 + 6], sa[8 * s2 + 7]);
;         pv.x = pk_bf16(sb[8 * s2 + 0], sb[8 * s2 + 1]); pv.y = pk_bf16(sb[8 * s2 + 2], sb[8 * s2 + 3]); pv.z = pk_bf16(sb[8 * s2 + 4], sb[8 * s2 + 5]); pv.w = pk_bf16(sb[8 * s2 + 6], sb[8 * s2 + 7]);
;         const bf16x8 pa_ = __builtin_bit_cast(bf16x8, pu), pb_ = __builtin_bit_cast(bf16x8, pv);
; #pragma unroll
;         for (int vt = 0; vt < 2; ++vt) {
;           const char* vp = cur + KBYTES + (vt * 32 + r) * VROW + (t2 * 32 + 16 * s2 + 4 * hh) * 2;
;           const uint2 lo = *(const uint2*)(vp), hi = *(const uint2*)(vp + 16);
;           uint4 vu; vu.x = lo.x; vu.y = lo.y; vu.z = hi.x; vu.w = hi.y;
;           const bf16x8 vf = __builtin_bit_cast(bf16x8, vu);
;           oa[vt] = MFMA(vf, pa_, oa[vt]);
;           ob[vt] = MFMA(vf, pb_, ob[vt]);
;         }
;       }
;       SB_;
;     }
;     SB_;
;     if (more) { char* nxt = smem + ((kt + 1) & 1) * STAGE; ATT64_STORE(nxt); }
;     __syncthreads();
	ds_write2_b64 v238, v[160:161], v[162:163] offset1:1
	s_nop 10
	v_exp_f32_e32 v168, v80
	v_exp_f32_e32 v213, v81
	v_exp_f32_e32 v233, v96
	v_exp_f32_e32 v96, v82
	v_exp_f32_e32 v234, v97
	v_exp_f32_e32 v97, v83
	v_add_f32_e32 v80, 0, v168
	v_exp_f32_e32 v235, v98
	v_exp_f32_e32 v98, v84
	v_add_f32_e32 v80, v213, v80
	v_exp_f32_e32 v236, v99
	v_exp_f32_e32 v99, v85
	v_add_f32_e32 v80, v96, v80
	v_add_f32_e32 v80, v97, v80
	v_add_f32_e32 v80, v98, v80
	v_exp_f32_e32 v237, v100
	v_exp_f32_e32 v241, v101
	v_exp_f32_e32 v100, v86
	v_exp_f32_e32 v101, v102
	v_exp_f32_e32 v102, v87
	v_exp_f32_e32 v103, v103
	v_exp_f32_e32 v218, v88
	v_exp_f32_e32 v219, v104
	v_exp_f32_e32 v104, v89
	v_exp_f32_e32 v105, v105
	v_exp_f32_e32 v226, v90
	v_exp_f32_e32 v227, v106
	v_exp_f32_e32 v106, v91
	v_exp_f32_e32 v107, v107
	v_exp_f32_e32 v228, v92
	v_exp_f32_e32 v229, v108
	v_exp_f32_e32 v108, v93
	v_exp_f32_e32 v109, v109
	v_exp_f32_e32 v230, v94
	v_exp_f32_e32 v231, v110
	v_exp_f32_e32 v110, v95
	v_exp_f32_e32 v111, v111
	v_add_f32_e32 v232, v99, v80
	v_cvt_pk_bf16_f32 v80, v186, v190
	v_cvt_pk_bf16_f32 v81, v192, v180
	v_cvt_pk_bf16_f32 v82, v182, v184
	v_cvt_pk_bf16_f32 v83, v176, v178
	v_cvt_pk_bf16_f32 v84, v187, v191
	v_cvt_pk_bf16_f32 v85, v193, v181
	v_mfma_f32_32x32x16_bf16 v[48:63], v[214:217], v[80:83], v[48:63]
	v_cvt_pk_bf16_f32 v86, v183, v185
	v_cvt_pk_bf16_f32 v87, v177, v179
	v_cvt_pk_bf16_f32 v88, v233, v234
	v_cvt_pk_bf16_f32 v89, v235, v236
	v_cvt_pk_bf16_f32 v90, v237, v241
	v_cvt_pk_bf16_f32 v91, v101, v103
	v_mfma_f32_32x32x16_bf16 v[16:31], v[222:225], v[80:83], v[16:31]
	ds_read2_b64 v[80:83], v239 offset0:8 offset1:10
	ds_read2_b64 v[246:249], v240 offset0:40 offset1:42
	v_mfma_f32_32x32x16_bf16 v[32:47], v[214:217], v[84:87], v[32:47]
	v_mfma_f32_32x32x16_bf16 v[0:15], v[222:225], v[84:87], v[0:15]
	v_cvt_pk_bf16_f32 v84, v168, v213
	v_cvt_pk_bf16_f32 v85, v96, v97
	v_cvt_pk_bf16_f32 v86, v98, v99
	v_cvt_pk_bf16_f32 v87, v100, v102
	s_waitcnt lgkmcnt(0)
	s_nop 0
	v_mfma_f32_32x32x16_bf16 v[48:63], v[80:83], v[84:87], v[48:63]
	v_mfma_f32_32x32x16_bf16 v[32:47], v[80:83], v[88:91], v[32:47]
	ds_read2_b64 v[92:95], v239 offset0:12 offset1:14
	ds_read2_b64 v[96:99], v240 offset0:44 offset1:46
	s_waitcnt lgkmcnt(2)
	v_mfma_f32_32x32x16_bf16 v[16:31], v[246:249], v[84:87], v[16:31]
	v_add_f32_e32 v84, 0, v233
	v_add_f32_e32 v84, v234, v84
	v_add_f32_e32 v84, v235, v84
	v_add_f32_e32 v84, v236, v84
	v_add_f32_e32 v84, v237, v84
	v_add_f32_e32 v233, v241, v84
	v_pk_add_f32 v[84:85], v[188:189], v[194:195]
	v_mfma_f32_32x32x16_bf16 v[0:15], v[246:249], v[88:91], v[0:15]
	v_add_f32_e64 v80, v186, v84
	v_add_f32_e64 v81, v187, v85
	v_add_f32_e64 v90, v100, v232
	v_add_f32_e64 v91, v101, v233
	v_add_f32_e64 v80, v190, v80
	v_add_f32_e64 v81, v191, v81
	v_pk_add_f32 v[90:91], v[102:103], v[90:91]
	v_pk_add_f32 v[84:85], v[192:193], v[80:81]
	v_cvt_pk_bf16_f32 v80, v218, v104
	v_pk_add_f32 v[84:85], v[180:181], v[84:85]
	v_cvt_pk_bf16_f32 v81, v226, v106
	v_pk_add_f32 v[84:85], v[182:183], v[84:85]
	v_cvt_pk_bf16_f32 v82, v228, v108
	v_cvt_pk_bf16_f32 v83, v230, v110
	v_pk_add_f32 v[88:89], v[184:185], v[84:85]
	v_cvt_pk_bf16_f32 v84, v219, v105
	v_cvt_pk_bf16_f32 v85, v227, v107
	v_cvt_pk_bf16_f32 v86, v229, v109
	v_cvt_pk_bf16_f32 v87, v231, v111
	v_pk_add_f32 v[90:91], v[218:219], v[90:91]
	s_waitcnt lgkmcnt(1)
	v_mfma_f32_32x32x16_bf16 v[48:63], v[92:95], v[80:83], v[48:63]
	v_add_f32_e64 v90, v104, v90
	v_add_f32_e64 v91, v105, v91
	v_add_f32_e64 v88, v176, v88
	v_add_f32_e64 v89, v177, v89
	v_add_f32_e64 v88, v178, v88
	v_add_f32_e64 v89, v179, v89
	v_pk_add_f32 v[88:89], v[166:167], v[88:89]
	v_mfma_f32_32x32x16_bf16 v[32:47], v[92:95], v[84:87], v[32:47]
	s_waitcnt lgkmcnt(0)
	v_mfma_f32_32x32x16_bf16 v[16:31], v[96:99], v[80:83], v[16:31]
	v_add_f32_e64 v80, v226, v90
	v_add_f32_e64 v81, v227, v91
	v_add_f32_e64 v80, v106, v80
	v_add_f32_e64 v81, v107, v81
	v_add_f32_e64 v80, v228, v80
	v_add_f32_e64 v81, v229, v81
	v_pk_add_f32 v[80:81], v[108:109], v[80:81]
	v_mfma_f32_32x32x16_bf16 v[0:15], v[96:99], v[84:87], v[0:15]
	v_add_f32_e64 v80, v230, v80
	v_add_f32_e64 v81, v231, v81
	v_add_f32_e64 v80, v110, v80
	v_add_f32_e64 v81, v111, v81
	v_add_f32_e64 v166, v88, v80
	v_add_f32_e64 v167, v89, v81
	s_add_i32 s8, s8, 1
	v_lshl_add_u64 v[170:171], v[170:171], 0, s[30:31]
	v_lshl_add_u64 v[172:173], v[172:173], 0, s[34:35]
	s_cmp_lg_u32 s8, 36
	v_lshl_add_u64 v[174:175], v[174:175], 0, s[34:35]
	s_waitcnt lgkmcnt(0)
	s_barrier
	s_cbranch_scc0 .LBB0_551
.LBB0_549:
	s_and_b32 s7, 1, s8
	s_cselect_b32 s6, 0x5200, 0
	s_cmp_eq_u32 s7, 1
	s_cselect_b32 s9, 0, 0x5200
	v_or_b32_e32 v80, s9, v211
	v_add_u32_e32 v80, v80, v210
	v_or_b32_e32 v81, s9, v164
	v_add_u32_e32 v168, v80, v212
	v_add3_u32 v213, v80, v207, v206
	v_add_u32_e32 v188, v168, v206
	v_add_u32_e32 v195, v81, v208
	ds_read_b128 v[176:179], v168
	ds_read_b128 v[242:245], v188 offset:32
	ds_read_b128 v[180:183], v168 offset:64
	ds_read_b128 v[246:249], v188 offset:96
	ds_read_b128 v[184:187], v168 offset:128
	v_add_u32_e32 v250, s6, v196
	v_add_u32_e32 v251, s6, v197
	v_add_u32_e32 v80, s6, v209
	v_add_u32_e32 v238, 0x3000, v80
	v_readfirstlane_b32 s4, v250
	s_mov_b32 m0, s4
	s_nop 0
	global_load_lds_dwordx4 v[172:173], off
	s_and_saveexec_b64 s[4:5], vcc
	s_cbranch_execz .LBB0_548
	v_readfirstlane_b32 s9, v251
	s_mov_b32 m0, s9
	s_nop 0
	global_load_lds_dwordx4 v[174:175], off
	s_branch .LBB0_548
